# attention PV: eight 5-MFMA blocks software-pipelined (next block LDS reads prefetched, two accumulators, scale/convert/store epilogue interleaved into the MFMA chain)
# baseline (speedup 1.0000x reference)
; #define LAS __attribute__((address_space(3)))
; __device__ __forceinline__ void attn_item(const Params& P, int half, int item, LAS unsigned char* lds, unsigned* ctr) {
;     ...
;     const int m0 = (16 * w < 96) ? 16 * w : 96;
;     f32x4 S[10];
; #pragma unroll
;     for (int jt = 0; jt < 10; ++jt) {
;         S[jt] = (f32x4){0.f, 0.f, 0.f, 0.f};
;         const LAS unsigned char* kr = Ks + (m0 + jt * 16 + c) * KSTR + 16 * g;
; #pragma unroll
;         for (int ks = 0; ks < 4; ++ks) { const bf16x8 a = *(const LAS bf16x8*)(kr + ks * 64); S[jt] = __builtin_amdgcn_mfma_f32_16x16x32_bf16(a, Qf[ks], S[jt], 0, 0, 0); }
;     }
.LBB0_539:
	s_or_b64 exec, exec, s[30:31]
	s_and_b32 s6, s6, -16
	v_and_b32_e32 v54, 15, v137
	s_min_i32 s6, s6, 0x60
	v_or_b32_e32 v18, s6, v54
	s_movk_i32 s7, 0x110
	v_mul_lo_u32 v18, v18, s7
	v_add3_u32 v55, 0, v194, v18
	ds_read_b128 v[204:207], v55
	ds_read_b128 v[208:211], v55 offset:64
	ds_read_b128 v[212:215], v55 offset:4416
	ds_read_b128 v[216:219], v55 offset:8768
	ds_read_b128 v[220:223], v55 offset:13120
	ds_read_b128 v[224:227], v55 offset:128
	s_and_b32 s5, s5, 0xff
	s_cmp_eq_u32 s5, 0
	s_cselect_b64 vcc, -1, 0
	s_mov_b32 s5, 0xff800000
	v_lshlrev_b32_e32 v194, 3, v136
	s_waitcnt lgkmcnt(5)
	v_mfma_f32_16x16x32_bf16 v[18:21], v[204:207], v[6:9], 0
	ds_read_b128 v[204:207], v55 offset:17472
	ds_read_b128 v[236:239], v55 offset:21824
	ds_read_b128 v[240:243], v55 offset:192
	s_waitcnt lgkmcnt(7)
	v_mfma_f32_16x16x32_bf16 v[18:21], v[208:211], v[14:17], v[18:21]
	ds_read_b128 v[208:211], v55 offset:26176
	ds_read_b128 v[244:247], v55 offset:30528
	ds_read_b128 v[176:179], v55 offset:4352
	s_waitcnt lgkmcnt(6)
	v_mfma_f32_16x16x32_bf16 v[18:21], v[224:227], v[2:5], v[18:21]
	ds_read_b128 v[224:227], v55 offset:34880
	ds_read_b128 v[180:183], v55 offset:4480
	ds_read_b128 v[184:187], v55 offset:4544
	s_waitcnt lgkmcnt(6)
	v_mfma_f32_16x16x32_bf16 v[18:21], v[240:243], v[10:13], v[18:21]
	ds_read_b128 v[240:243], v55 offset:8704
	ds_read_b128 v[188:191], v55 offset:8832
	s_waitcnt lgkmcnt(5)
	v_mfma_f32_16x16x32_bf16 v[22:25], v[176:179], v[6:9], 0
	v_mfma_f32_16x16x32_bf16 v[22:25], v[212:215], v[14:17], v[22:25]
	ds_read_b128 v[212:215], v55 offset:8896
	s_waitcnt lgkmcnt(4)
	v_mfma_f32_16x16x32_bf16 v[22:25], v[180:183], v[2:5], v[22:25]
	ds_read_b128 v[176:179], v55 offset:13056
	s_waitcnt lgkmcnt(4)
	v_mfma_f32_16x16x32_bf16 v[22:25], v[184:187], v[10:13], v[22:25]
	ds_read_b128 v[180:183], v55 offset:13184
	s_waitcnt lgkmcnt(4)
	v_mfma_f32_16x16x32_bf16 v[26:29], v[240:243], v[6:9], 0
	v_mfma_f32_16x16x32_bf16 v[26:29], v[216:219], v[14:17], v[26:29]
	ds_read_b128 v[216:219], v55 offset:13248
	s_waitcnt lgkmcnt(4)
	v_mfma_f32_16x16x32_bf16 v[26:29], v[188:191], v[2:5], v[26:29]
	ds_read_b128 v[240:243], v55 offset:17408
	s_waitcnt lgkmcnt(4)
	v_mfma_f32_16x16x32_bf16 v[26:29], v[212:215], v[10:13], v[26:29]
	ds_read_b128 v[212:215], v55 offset:17536
	s_waitcnt lgkmcnt(4)
	v_mfma_f32_16x16x32_bf16 v[30:33], v[176:179], v[6:9], 0
	v_mfma_f32_16x16x32_bf16 v[30:33], v[220:223], v[14:17], v[30:33]
	ds_read_b128 v[220:223], v55 offset:17600
	s_waitcnt lgkmcnt(4)
	v_mfma_f32_16x16x32_bf16 v[30:33], v[180:183], v[2:5], v[30:33]
	ds_read_b128 v[176:179], v55 offset:21760
	s_waitcnt lgkmcnt(4)
	v_mfma_f32_16x16x32_bf16 v[30:33], v[216:219], v[10:13], v[30:33]
	ds_read_b128 v[216:219], v55 offset:21888
	s_waitcnt lgkmcnt(4)
	v_mfma_f32_16x16x32_bf16 v[34:37], v[240:243], v[6:9], 0
	v_mfma_f32_16x16x32_bf16 v[34:37], v[204:207], v[14:17], v[34:37]
	ds_read_b128 v[204:207], v55 offset:21952
	s_waitcnt lgkmcnt(4)
	v_mfma_f32_16x16x32_bf16 v[34:37], v[212:215], v[2:5], v[34:37]
	ds_read_b128 v[212:215], v55 offset:26112
	s_waitcnt lgkmcnt(4)
	v_mfma_f32_16x16x32_bf16 v[34:37], v[220:223], v[10:13], v[34:37]
	ds_read_b128 v[220:223], v55 offset:26240
	s_waitcnt lgkmcnt(4)
	v_mfma_f32_16x16x32_bf16 v[38:41], v[176:179], v[6:9], 0
	v_mfma_f32_16x16x32_bf16 v[38:41], v[236:239], v[14:17], v[38:41]
	ds_read_b128 v[236:239], v55 offset:26304
	s_waitcnt lgkmcnt(4)
	v_mfma_f32_16x16x32_bf16 v[38:41], v[216:219], v[2:5], v[38:41]
	ds_read_b128 v[216:219], v55 offset:30464
	s_waitcnt lgkmcnt(4)
	v_mfma_f32_16x16x32_bf16 v[38:41], v[204:207], v[10:13], v[38:41]
	ds_read_b128 v[204:207], v55 offset:30592
	s_waitcnt lgkmcnt(4)
	v_mfma_f32_16x16x32_bf16 v[42:45], v[212:215], v[6:9], 0
	v_mfma_f32_16x16x32_bf16 v[42:45], v[208:211], v[14:17], v[42:45]
	ds_read_b128 v[208:211], v55 offset:30656
	s_waitcnt lgkmcnt(4)
	v_mfma_f32_16x16x32_bf16 v[42:45], v[220:223], v[2:5], v[42:45]
	ds_read_b128 v[212:215], v55 offset:34816
	s_waitcnt lgkmcnt(4)
	v_mfma_f32_16x16x32_bf16 v[42:45], v[236:239], v[10:13], v[42:45]
	ds_read_b128 v[220:223], v55 offset:34944
	s_waitcnt lgkmcnt(4)
	v_mfma_f32_16x16x32_bf16 v[46:49], v[216:219], v[6:9], 0
	v_mfma_f32_16x16x32_bf16 v[46:49], v[244:247], v[14:17], v[46:49]
	ds_read_b128 v[216:219], v55 offset:35008
	s_waitcnt lgkmcnt(4)
	v_mfma_f32_16x16x32_bf16 v[46:49], v[204:207], v[2:5], v[46:49]
	ds_read_b128 v[204:207], v55 offset:39168
	s_waitcnt lgkmcnt(4)
	v_mfma_f32_16x16x32_bf16 v[46:49], v[208:211], v[10:13], v[46:49]
	ds_read_b128 v[208:211], v55 offset:39232
	s_waitcnt lgkmcnt(4)
	v_mfma_f32_16x16x32_bf16 v[50:53], v[212:215], v[6:9], 0
	v_mfma_f32_16x16x32_bf16 v[50:53], v[224:227], v[14:17], v[50:53]
	ds_read_b128 v[212:215], v55 offset:39296
	s_waitcnt lgkmcnt(4)
	v_mfma_f32_16x16x32_bf16 v[50:53], v[220:223], v[2:5], v[50:53]
	ds_read_b128 v[220:223], v55 offset:39360
	s_waitcnt lgkmcnt(4)
	v_mfma_f32_16x16x32_bf16 v[50:53], v[216:219], v[10:13], v[50:53]
	s_nop 0
	s_waitcnt lgkmcnt(3)
	v_mfma_f32_16x16x32_bf16 v[6:9], v[204:207], v[6:9], 0
	s_nop 0
	s_waitcnt lgkmcnt(2)
	v_mfma_f32_16x16x32_bf16 v[6:9], v[208:211], v[14:17], v[6:9]
	s_nop 0
	s_waitcnt lgkmcnt(1)
	v_mfma_f32_16x16x32_bf16 v[2:5], v[212:215], v[2:5], v[6:9]
	s_nop 4
	s_nop 0
	s_waitcnt lgkmcnt(0)
; __device__ __forceinline__ void attn_item(const Params& P, int half, int item, LAS unsigned char* lds, unsigned* ctr) {
;     ...
;     float mx = -INFINITY;
;     const int dbase = qi + 128 - m0 - 4 * g;
;     const unsigned dlim = (unsigned)((n == 0) ? (qi < 128 ? qi : 128) : 128);
; #pragma unroll
;     for (int jt = 0; jt < 10; ++jt)
; #pragma unroll
;         for (int jj = 0; jj < 4; ++jj) { const bool ok = (unsigned)(dbase - (jt * 16 + jj)) <= dlim;
;             const float s = ok ? S[jt][jj] : -INFINITY; S[jt][jj] = s; mx = fmaxf(mx, s); }
;     mx = fmaxf(mx, __shfl_xor(mx, 16)); mx = fmaxf(mx, __shfl_xor(mx, 32));
	v_mfma_f32_16x16x32_bf16 v[2:5], v[220:223], v[10:13], v[2:5]
	v_lshlrev_b32_e32 v6, 2, v136
	v_min_i32_e32 v7, 0x80, v138
	v_mov_b32_e32 v8, 0x80
	v_or_b32_e32 v55, s6, v6
	v_cndmask_b32_e32 v7, v8, v7, vcc
	v_add_u32_e32 v8, 0x80, v138
	v_sub_u32_e32 v9, v8, v55
	v_bitop3_b32 v6, s6, v6, s6 bitop3:3
	v_cmp_le_u32_e32 vcc, v9, v7
	v_add_u32_e32 v8, v8, v6
	v_sub_u32_e32 v11, v138, v55
	v_cndmask_b32_e32 v9, v235, v18, vcc
	v_cmp_le_u32_e32 vcc, v8, v7
	v_add_u32_e32 v12, 0x7e, v11
	v_add_u32_e32 v13, 0x7d, v11
	v_cndmask_b32_e32 v8, v235, v19, vcc
	v_cmp_le_u32_e32 vcc, v12, v7
	v_add_u32_e32 v14, 0x70, v11
	v_add_u32_e32 v15, 0x6f, v11
	v_cndmask_b32_e32 v12, v235, v20, vcc
	v_cmp_le_u32_e32 vcc, v13, v7
	v_add_u32_e32 v16, 0x6e, v11
	v_add_u32_e32 v17, 0x6d, v11
	v_cndmask_b32_e32 v13, v235, v21, vcc
	v_cmp_le_u32_e32 vcc, v14, v7
	v_add_u32_e32 v18, 0x60, v11
	v_add_u32_e32 v19, 0x5f, v11
	v_cndmask_b32_e32 v14, v235, v22, vcc
	v_cmp_le_u32_e32 vcc, v15, v7
	v_add_u32_e32 v20, 0x5e, v11
	v_add_u32_e32 v21, 0x5d, v11
	v_cndmask_b32_e32 v15, v235, v23, vcc
	v_cmp_le_u32_e32 vcc, v16, v7
	v_add_u32_e32 v22, 0x50, v11
	v_add_u32_e32 v23, 0x4f, v11
	v_cndmask_b32_e32 v16, v235, v24, vcc
	v_cmp_le_u32_e32 vcc, v17, v7
	v_max3_f32 v10, v9, s5, v8
	v_max3_f32 v10, v10, v12, v13
	v_cndmask_b32_e32 v17, v235, v25, vcc
	v_cmp_le_u32_e32 vcc, v18, v7
	v_max3_f32 v10, v10, v14, v15
	v_max3_f32 v10, v10, v16, v17
	v_cndmask_b32_e32 v18, v235, v26, vcc
	v_cmp_le_u32_e32 vcc, v19, v7
	v_add_u32_e32 v6, v138, v6
	v_readlane_b32 s5, v255, 16
	v_cndmask_b32_e32 v19, v235, v27, vcc
	v_cmp_le_u32_e32 vcc, v20, v7
	v_max3_f32 v10, v10, v18, v19
	s_nop 0
	v_cndmask_b32_e32 v20, v235, v28, vcc
	v_cmp_le_u32_e32 vcc, v21, v7
	s_nop 1
	v_cndmask_b32_e32 v21, v235, v29, vcc
	v_cmp_le_u32_e32 vcc, v22, v7
	v_max3_f32 v10, v10, v20, v21
	s_nop 0
	v_cndmask_b32_e32 v22, v235, v30, vcc
	v_cmp_le_u32_e32 vcc, v23, v7
	v_add_u32_e32 v23, 0x4e, v11
	s_nop 0
	v_cndmask_b32_e32 v25, v235, v31, vcc
	v_cmp_le_u32_e32 vcc, v23, v7
	v_add_u32_e32 v23, 0x4d, v11
	v_max3_f32 v10, v10, v22, v25
	v_cndmask_b32_e32 v26, v235, v32, vcc
	v_cmp_le_u32_e32 vcc, v23, v7
	v_add_u32_e32 v23, 64, v11
	s_nop 0
	v_cndmask_b32_e32 v27, v235, v33, vcc
	v_cmp_le_u32_e32 vcc, v23, v7
	v_add_u32_e32 v23, 63, v11
	v_max3_f32 v10, v10, v26, v27
	v_cndmask_b32_e32 v28, v235, v34, vcc
	v_cmp_le_u32_e32 vcc, v23, v7
	v_add_u32_e32 v23, 62, v11
	s_nop 0
	v_cndmask_b32_e32 v29, v235, v35, vcc
	v_cmp_le_u32_e32 vcc, v23, v7
	v_add_u32_e32 v23, 61, v11
	v_max3_f32 v10, v10, v28, v29
	v_cndmask_b32_e32 v30, v235, v36, vcc
	v_cmp_le_u32_e32 vcc, v23, v7
	v_add_u32_e32 v23, 48, v11
	s_nop 0
	v_cndmask_b32_e32 v31, v235, v37, vcc
	v_cmp_le_u32_e32 vcc, v23, v7
	v_add_u32_e32 v23, 47, v11
	v_max3_f32 v10, v10, v30, v31
	v_cndmask_b32_e32 v34, v235, v38, vcc
	v_cmp_le_u32_e32 vcc, v23, v7
	v_add_u32_e32 v23, 46, v11
	s_nop 0
	v_cndmask_b32_e32 v35, v235, v39, vcc
	v_cmp_le_u32_e32 vcc, v23, v7
	v_add_u32_e32 v23, 45, v11
	v_max3_f32 v10, v10, v34, v35
	v_cndmask_b32_e32 v36, v235, v40, vcc
	v_cmp_le_u32_e32 vcc, v23, v7
	v_add_u32_e32 v23, 32, v11
	s_nop 0
	v_cndmask_b32_e32 v37, v235, v41, vcc
	v_cmp_le_u32_e32 vcc, v23, v7
	v_add_u32_e32 v23, 31, v11
	v_max3_f32 v10, v10, v36, v37
	v_cndmask_b32_e32 v38, v235, v42, vcc
	v_cmp_le_u32_e32 vcc, v23, v7
	v_add_u32_e32 v23, 30, v11
	s_nop 0
	v_cndmask_b32_e32 v39, v235, v43, vcc
	v_cmp_le_u32_e32 vcc, v23, v7
	v_add_u32_e32 v23, 29, v11
	v_max3_f32 v10, v10, v38, v39
	v_cndmask_b32_e32 v40, v235, v44, vcc
	v_cmp_le_u32_e32 vcc, v23, v7
	v_add_u32_e32 v23, 16, v11
	s_nop 0
	v_cndmask_b32_e32 v41, v235, v45, vcc
	v_cmp_le_u32_e32 vcc, v23, v7
	v_add_u32_e32 v23, 15, v11
	v_max3_f32 v10, v10, v40, v41
	v_cndmask_b32_e32 v42, v235, v46, vcc
	v_cmp_le_u32_e32 vcc, v23, v7
	v_add_u32_e32 v23, 14, v11
	s_nop 0
	v_cndmask_b32_e32 v43, v235, v47, vcc
	v_cmp_le_u32_e32 vcc, v23, v7
	v_add_u32_e32 v23, 13, v11
	v_max3_f32 v10, v10, v42, v43
	v_cndmask_b32_e32 v44, v235, v48, vcc
	v_cmp_le_u32_e32 vcc, v23, v7
	s_nop 1
	v_cndmask_b32_e32 v45, v235, v49, vcc
	v_cmp_le_u32_e32 vcc, v11, v7
	v_max3_f32 v10, v10, v44, v45
	s_nop 0
	v_cndmask_b32_e32 v46, v235, v50, vcc
	v_cmp_le_u32_e32 vcc, v6, v7
	s_nop 1
	v_cndmask_b32_e32 v47, v235, v51, vcc
	v_max3_f32 v6, v10, v46, v47
	v_add_u32_e32 v10, -2, v11
	v_cmp_le_u32_e32 vcc, v10, v7
	v_add_u32_e32 v10, -3, v11
	s_nop 0
	v_cndmask_b32_e32 v48, v235, v52, vcc
	v_cmp_le_u32_e32 vcc, v10, v7
	v_add_u32_e32 v10, -16, v11
	s_nop 0
	v_cndmask_b32_e32 v49, v235, v53, vcc
	v_cmp_le_u32_e32 vcc, v10, v7
	v_max3_f32 v6, v6, v48, v49
	s_nop 0
	v_cndmask_b32_e32 v50, v235, v2, vcc
	v_subrev_u32_e32 v2, 17, v11
	v_cmp_le_u32_e32 vcc, v2, v7
	s_nop 1
	v_cndmask_b32_e32 v51, v235, v3, vcc
	v_subrev_u32_e32 v3, 18, v11
	v_cmp_le_u32_e32 vcc, v3, v7
	v_subrev_u32_e32 v3, 19, v11
	v_max3_f32 v2, v6, v50, v51
	v_cndmask_b32_e32 v52, v235, v4, vcc
	v_and_b32_e32 v4, 64, v230
	v_cmp_le_u32_e32 vcc, v3, v7
	v_xor_b32_e32 v3, 16, v230
	v_add_u32_e32 v4, 64, v4
	v_cndmask_b32_e32 v53, v235, v5, vcc
	v_cmp_lt_i32_e32 vcc, v3, v4
	v_max3_f32 v2, v2, v52, v53
	s_nop 0
	v_cndmask_b32_e32 v3, v230, v3, vcc
	v_lshlrev_b32_e32 v56, 2, v3
	v_mov_b32_e32 v3, v2
	s_nop 1
	v_permlane16_swap_b32_e32 v3, v2
	s_nop 1
	s_waitcnt lgkmcnt(0)
	v_max_f32_e32 v3, v3, v3
	v_max_f32_e32 v2, v2, v3
	v_xor_b32_e32 v3, 32, v230
	v_cmp_lt_i32_e32 vcc, v3, v4
	s_nop 1
	v_cndmask_b32_e32 v3, v230, v3, vcc
	v_lshlrev_b32_e32 v57, 2, v3
	v_mov_b32_e32 v3, v2
	s_nop 1
	v_permlane32_swap_b32_e32 v3, v2
	s_nop 1
	s_waitcnt lgkmcnt(0)
; #define LAS __attribute__((address_space(3)))
; __device__ __forceinline__ unsigned cvt_pk_bf16(float lo, float hi) { unsigned r; asm volatile("v_cvt_pk_bf16_f32 %0, %1, %2" : "=v"(r) : "v"(lo), "v"(hi)); return r; }
; __device__ __forceinline__ void attn_item(const Params& P, int half, int item, LAS unsigned char* lds, unsigned* ctr) {
;     ...
;     float den = 0.f;
; #pragma unroll
;     for (int jt = 0; jt < 10; ++jt) { const f32x4 d = S[jt] - mx; f32x4 p; p[0] = __builtin_amdgcn_exp2f(d[0]); p[1] = __builtin_amdgcn_exp2f(d[1]); p[2] = __builtin_amdgcn_exp2f(d[2]); p[3] = __builtin_amdgcn_exp2f(d[3]);
;         S[jt] = p; den += (p[0] + p[1]) + (p[2] + p[3]); }
;     den += __shfl_xor(den, 16); den += __shfl_xor(den, 32);
;     bf16x8 Pf[5];
; #pragma unroll
;     for (int k5 = 0; k5 < 5; ++k5) { u32x4 pw; pw.x = cvt_pk_bf16(S[2 * k5][0], S[2 * k5][1]); pw.y = cvt_pk_bf16(S[2 * k5][2], S[2 * k5][3]); pw.z = cvt_pk_bf16(S[2 * k5 + 1][0], S[2 * k5 + 1][1]); pw.w = cvt_pk_bf16(S[2 * k5 + 1][2], S[2 * k5 + 1][3]); Pf[k5] = as_bf16x8(pw); }
;     const float inv = 1.0f / den;
;     bf16_t* op = Z + (size_t)qrow * ZC + colq + 4 * g;
; #pragma unroll
;     for (int dt = 0; dt < 8; ++dt) {
;         f32x4 O = (f32x4){0.f, 0.f, 0.f, 0.f};
;         const LAS unsigned char* vr = Vt + (dt * 16 + c) * VSTR + (m0 + 4 * g) * 2;
; #pragma unroll
;         for (int k5 = 0; k5 < 5; ++k5) { const u32x2 lo = *(const LAS u32x2*)(vr + k5 * 64), hi = *(const LAS u32x2*)(vr + k5 * 64 + 32);
;             const bf16x8 a = as_bf16x8((u32x4){lo.x, lo.y, hi.x, hi.y}); O = __builtin_amdgcn_mfma_f32_16x16x32_bf16(a, Pf[k5], O, 0, 0, 0); }
	v_max_f32_e32 v3, v3, v3
	v_max_f32_e32 v24, v2, v3
	v_sub_f32_e32 v2, v13, v24
	v_sub_f32_e32 v3, v12, v24
	v_sub_f32_e32 v5, v8, v24
	v_sub_f32_e32 v4, v9, v24
	v_exp_f32_e32 v4, v4
	v_exp_f32_e32 v6, v5
	v_exp_f32_e32 v5, v3
	v_exp_f32_e32 v7, v2
	v_sub_f32_e32 v9, v16, v24
	v_sub_f32_e32 v10, v15, v24
	v_sub_f32_e32 v8, v14, v24
	v_pk_add_f32 v[2:3], v[4:5], v[6:7]
	v_exp_f32_e32 v8, v8
	v_add_f32_e32 v2, v2, v3
	v_add_f32_e32 v3, 0, v2
	v_sub_f32_e32 v2, v17, v24
	v_exp_f32_e32 v10, v10
	v_exp_f32_e32 v9, v9
	v_exp_f32_e32 v11, v2
	v_sub_f32_e32 v2, v21, v24
	v_sub_f32_e32 v14, v19, v24
	v_sub_f32_e32 v15, v18, v24
	v_pk_add_f32 v[12:13], v[8:9], v[10:11]
	v_exp_f32_e32 v58, v15
	v_pk_add_f32 v[12:13], v[12:13], v[12:13] op_sel_hi:[0,1]
	v_sub_f32_e32 v12, v20, v24
	v_exp_f32_e32 v59, v14
	v_exp_f32_e32 v60, v12
	v_exp_f32_e32 v61, v2
	v_sub_f32_e32 v2, v27, v24
	v_sub_f32_e32 v12, v26, v24
	v_sub_f32_e32 v14, v25, v24
	v_sub_f32_e32 v15, v22, v24
	v_exp_f32_e32 v16, v15
	v_exp_f32_e32 v22, v14
	v_exp_f32_e32 v12, v12
	v_exp_f32_e32 v2, v2
	v_add_f32_e32 v17, v58, v59
	v_add_f32_e32 v23, v60, v61
	v_pk_add_f32 v[14:15], v[16:17], v[22:23]
	v_pk_add_f32 v[18:19], v[12:13], v[2:3]
	v_sub_f32_e32 v3, v31, v24
	v_pk_add_f32 v[14:15], v[14:15], v[18:19]
	v_sub_f32_e32 v13, v30, v24
	v_pk_add_f32 v[26:27], v[14:15], v[14:15] op_sel_hi:[0,1]
	v_sub_f32_e32 v14, v29, v24
	v_sub_f32_e32 v15, v28, v24
	v_exp_f32_e32 v28, v15
	v_exp_f32_e32 v30, v14
	v_exp_f32_e32 v29, v13
	v_exp_f32_e32 v31, v3
	v_sub_f32_e32 v3, v37, v24
	v_sub_f32_e32 v13, v36, v24
	v_exp_f32_e32 v13, v13
	v_pk_add_f32 v[14:15], v[28:29], v[30:31]
	v_exp_f32_e32 v3, v3
	v_pk_add_f32 v[32:33], v[14:15], v[14:15] op_sel_hi:[0,1]
	v_sub_f32_e32 v14, v35, v24
	v_sub_f32_e32 v15, v34, v24
	v_exp_f32_e32 v23, v15
	v_exp_f32_e32 v25, v14
	v_sub_f32_e32 v14, v41, v24
	v_sub_f32_e32 v15, v40, v24
	v_sub_f32_e32 v17, v39, v24
	v_sub_f32_e32 v18, v38, v24
	v_exp_f32_e32 v34, v18
	v_exp_f32_e32 v36, v17
	v_exp_f32_e32 v32, v15
	v_exp_f32_e32 v26, v14
	v_add_f32_e32 v35, v23, v25
	v_add_f32_e32 v37, v13, v3
	v_pk_add_f32 v[14:15], v[34:35], v[36:37]
	v_pk_add_f32 v[18:19], v[32:33], v[26:27]
	v_sub_f32_e32 v17, v43, v24
	v_pk_add_f32 v[14:15], v[14:15], v[18:19]
	v_sub_f32_e32 v18, v42, v24
	v_pk_add_f32 v[38:39], v[14:15], v[14:15] op_sel_hi:[0,1]
	v_sub_f32_e32 v14, v45, v24
	v_sub_f32_e32 v15, v44, v24
	v_exp_f32_e32 v40, v18
	v_exp_f32_e32 v42, v17
	v_exp_f32_e32 v41, v15
	v_exp_f32_e32 v43, v14
	v_sub_f32_e32 v17, v47, v24
	v_sub_f32_e32 v18, v46, v24
	v_exp_f32_e32 v27, v18
	v_pk_add_f32 v[14:15], v[40:41], v[42:43]
	v_exp_f32_e32 v33, v17
	v_pk_add_f32 v[44:45], v[14:15], v[14:15] op_sel_hi:[0,1]
	v_sub_f32_e32 v14, v49, v24
	v_sub_f32_e32 v15, v48, v24
	v_exp_f32_e32 v35, v15
	v_exp_f32_e32 v37, v14
	v_sub_f32_e32 v14, v53, v24
	v_sub_f32_e32 v15, v52, v24
	v_sub_f32_e32 v17, v51, v24
	v_sub_f32_e32 v18, v50, v24
	v_exp_f32_e32 v46, v18
	v_exp_f32_e32 v48, v17
	v_exp_f32_e32 v44, v15
	v_exp_f32_e32 v38, v14
	v_add_f32_e32 v47, v27, v33
	v_add_f32_e32 v49, v35, v37
	v_pk_add_f32 v[14:15], v[46:47], v[48:49]
	v_pk_add_f32 v[18:19], v[44:45], v[38:39]
	s_nop 0
	v_pk_add_f32 v[14:15], v[14:15], v[18:19]
	v_cvt_pk_bf16_f32 v18, v4, v6
	v_cvt_pk_bf16_f32 v19, v5, v7
	v_cvt_pk_bf16_f32 v20, v8, v10
	v_cvt_pk_bf16_f32 v21, v9, v11
	s_nop 0
	v_add_f32_e32 v14, v14, v15
	v_mov_b32_e32 v15, v14
	s_nop 1
	v_permlane16_swap_b32_e32 v15, v14
	s_nop 1
	s_waitcnt lgkmcnt(0)
	v_add_f32_e32 v39, v14, v15
	ds_bpermute_b32 v45, v57, v39
	v_cvt_pk_bf16_f32 v14, v58, v59
	v_cvt_pk_bf16_f32 v15, v60, v61
	v_cvt_pk_bf16_f32 v16, v16, v22
	v_cvt_pk_bf16_f32 v17, v12, v2
	v_cvt_pk_bf16_f32 v10, v28, v30
	v_cvt_pk_bf16_f32 v11, v29, v31
	v_cvt_pk_bf16_f32 v12, v23, v25
	s_waitcnt lgkmcnt(0)
	v_add_f32_e32 v25, v39, v45
	v_div_scale_f32 v22, s[6:7], v25, v25, 1.0
	v_rcp_f32_e32 v23, v22
	v_cvt_pk_bf16_f32 v13, v13, v3
	v_cvt_pk_bf16_f32 v6, v34, v36
	v_cvt_pk_bf16_f32 v7, v32, v26
	v_cvt_pk_bf16_f32 v8, v40, v42
	v_cvt_pk_bf16_f32 v9, v41, v43
	s_nop 0
	v_fma_f32 v26, -v22, v23, 1.0
	v_fmac_f32_e32 v23, v26, v23
	v_div_scale_f32 v26, vcc, 1.0, v25, 1.0
	v_cvt_pk_bf16_f32 v2, v27, v33
	v_mul_f32_e32 v27, v26, v23
	v_fma_f32 v28, -v22, v27, v26
	v_fmac_f32_e32 v27, v28, v23
	v_fma_f32 v22, -v22, v27, v26
	v_div_fmas_f32 v22, v22, v23, v27
	v_lshlrev_b32_e32 v27, 1, v55
	v_mul_u32_u24_e32 v28, 0x210, v54
	v_add3_u32 v27, s5, v27, v28
	v_cvt_pk_bf16_f32 v3, v35, v37
	v_cvt_pk_bf16_f32 v4, v46, v48
	v_cvt_pk_bf16_f32 v5, v44, v38
	ds_read2_b64 v[204:207], v27 offset1:4
	ds_read2_b64 v[208:211], v27 offset0:8 offset1:12
	ds_read2_b64 v[212:215], v27 offset0:16 offset1:20
	ds_read2_b64 v[216:219], v27 offset0:24 offset1:28
	ds_read2_b64 v[220:223], v27 offset0:32 offset1:36
	v_add_u32_e32 v156, 0x2100, v27
	ds_read2_b64 v[176:179], v156 offset1:4
	ds_read2_b64 v[180:183], v156 offset0:8 offset1:12
	ds_read2_b64 v[184:187], v156 offset0:16 offset1:20
	ds_read2_b64 v[188:191], v156 offset0:24 offset1:28
	ds_read2_b64 v[172:175], v156 offset0:32 offset1:36
	s_waitcnt lgkmcnt(9)
	v_mfma_f32_16x16x32_bf16 v[28:31], v[204:207], v[18:21], 0
	v_div_fixup_f32 v26, v22, v25, 1.0
	v_lshl_add_u64 v[22:23], v[130:131], 0, v[194:195]
	v_and_b32_e32 v192, 16, v230
	v_lshrrev_b32_e32 v193, 1, v192
	v_add_u32_e32 v192, v192, v193
	v_mov_b32_e32 v193, 0
	v_lshl_add_u64 v[192:193], v[22:23], 0, v[192:193]
	s_waitcnt lgkmcnt(8)
	v_mfma_f32_16x16x32_bf16 v[28:31], v[208:211], v[14:17], v[28:31]
	v_cmp_eq_u32_e32 vcc, 0, v136
	s_waitcnt lgkmcnt(7)
	v_mfma_f32_16x16x32_bf16 v[28:31], v[212:215], v[10:13], v[28:31]
	s_waitcnt lgkmcnt(6)
; #define LAS __attribute__((address_space(3)))
; __device__ __forceinline__ unsigned cvt_pk_bf16(float lo, float hi) { unsigned r; asm volatile("v_cvt_pk_bf16_f32 %0, %1, %2" : "=v"(r) : "v"(lo), "v"(hi)); return r; }
; __device__ __forceinline__ void attn_item(const Params& P, int half, int item, LAS unsigned char* lds, unsigned* ctr) {
;     ...
;     const float inv = 1.0f / den;
;     bf16_t* op = Z + (size_t)qrow * ZC + colq + 4 * g;
; #pragma unroll
;     for (int dt = 0; dt < 8; ++dt) {
;         f32x4 O = (f32x4){0.f, 0.f, 0.f, 0.f};
;         const LAS unsigned char* vr = Vt + (dt * 16 + c) * VSTR + (m0 + 4 * g) * 2;
; #pragma unroll
;         for (int k5 = 0; k5 < 5; ++k5) { const u32x2 lo = *(const LAS u32x2*)(vr + k5 * 64), hi = *(const LAS u32x2*)(vr + k5 * 64 + 32);
;             const bf16x8 a = as_bf16x8((u32x4){lo.x, lo.y, hi.x, hi.y}); O = __builtin_amdgcn_mfma_f32_16x16x32_bf16(a, Pf[k5], O, 0, 0, 0); }
;         u32x2 ow; ow.x = cvt_pk_bf16(O[0] * inv, O[1] * inv); ow.y = cvt_pk_bf16(O[2] * inv, O[3] * inv);
;         *(u32x2*)(op + dt * 16) = ow;
;     }
	v_mfma_f32_16x16x32_bf16 v[28:31], v[216:219], v[6:9], v[28:31]
	s_waitcnt lgkmcnt(5)
	v_mfma_f32_16x16x32_bf16 v[28:31], v[220:223], v[2:5], v[28:31]
	v_add_u32_e32 v157, 0x4200, v27
	ds_read2_b64 v[204:207], v157 offset1:4
	ds_read2_b64 v[208:211], v157 offset0:8 offset1:12
	ds_read2_b64 v[212:215], v157 offset0:16 offset1:20
	ds_read2_b64 v[216:219], v157 offset0:24 offset1:28
	ds_read2_b64 v[220:223], v157 offset0:32 offset1:36
	s_waitcnt lgkmcnt(9)
	v_mfma_f32_16x16x32_bf16 v[152:155], v[176:179], v[18:21], 0
	s_nop 3
	v_mul_f32_e32 v28, v26, v28
	v_mul_f32_e32 v29, v26, v29
	s_waitcnt lgkmcnt(8)
	v_mfma_f32_16x16x32_bf16 v[152:155], v[180:183], v[14:17], v[152:155]
	v_cvt_pk_bf16_f32 v28, v28, v29
	v_mul_f32_e32 v29, v26, v30
	s_waitcnt lgkmcnt(7)
	v_mfma_f32_16x16x32_bf16 v[152:155], v[184:187], v[10:13], v[152:155]
	v_mul_f32_e32 v30, v26, v31
	v_cvt_pk_bf16_f32 v29, v29, v30
	s_waitcnt lgkmcnt(6)
	v_mfma_f32_16x16x32_bf16 v[152:155], v[188:191], v[6:9], v[152:155]
	v_mov_b32_e32 v248, v28
	v_mov_b32_e32 v249, v29
	s_waitcnt lgkmcnt(5)
	v_mfma_f32_16x16x32_bf16 v[152:155], v[172:175], v[2:5], v[152:155]
	v_add_u32_e32 v156, 0x6300, v27
	ds_read2_b64 v[176:179], v156 offset1:4
	ds_read2_b64 v[180:183], v156 offset0:8 offset1:12
	ds_read2_b64 v[184:187], v156 offset0:16 offset1:20
	ds_read2_b64 v[188:191], v156 offset0:24 offset1:28
	ds_read2_b64 v[172:175], v156 offset0:32 offset1:36
	s_waitcnt lgkmcnt(9)
	v_mfma_f32_16x16x32_bf16 v[28:31], v[204:207], v[18:21], 0
	s_nop 3
	v_mul_f32_e32 v152, v26, v152
	v_mul_f32_e32 v153, v26, v153
	s_waitcnt lgkmcnt(8)
	v_mfma_f32_16x16x32_bf16 v[28:31], v[208:211], v[14:17], v[28:31]
	v_cvt_pk_bf16_f32 v152, v152, v153
	v_mul_f32_e32 v153, v26, v154
	s_waitcnt lgkmcnt(7)
	v_mfma_f32_16x16x32_bf16 v[28:31], v[212:215], v[10:13], v[28:31]
	v_mul_f32_e32 v154, v26, v155
	v_cvt_pk_bf16_f32 v153, v153, v154
	s_waitcnt lgkmcnt(6)
	v_mfma_f32_16x16x32_bf16 v[28:31], v[216:219], v[6:9], v[28:31]
	v_mov_b32_e32 v154, v152
	v_mov_b32_e32 v155, v153
	v_mov_b32_e32 v152, v248
	v_mov_b32_e32 v153, v249
	s_waitcnt lgkmcnt(5)
	v_mfma_f32_16x16x32_bf16 v[28:31], v[220:223], v[2:5], v[28:31]
	s_nop 1
	v_permlane16_swap_b32_e32 v152, v154
	v_permlane16_swap_b32_e32 v153, v155
	global_store_dwordx4 v[192:193], v[152:155], off
	s_nop 1
	v_add_u32_e32 v157, 0x8400, v27
	ds_read2_b64 v[204:207], v157 offset1:4
	ds_read2_b64 v[208:211], v157 offset0:8 offset1:12
	ds_read2_b64 v[212:215], v157 offset0:16 offset1:20
	ds_read2_b64 v[216:219], v157 offset0:24 offset1:28
	ds_read2_b64 v[220:223], v157 offset0:32 offset1:36
	s_waitcnt lgkmcnt(9)
	v_mfma_f32_16x16x32_bf16 v[152:155], v[176:179], v[18:21], 0
	s_nop 3
	v_mul_f32_e32 v28, v26, v28
	v_mul_f32_e32 v29, v26, v29
	s_waitcnt lgkmcnt(8)
	v_mfma_f32_16x16x32_bf16 v[152:155], v[180:183], v[14:17], v[152:155]
	v_cvt_pk_bf16_f32 v28, v28, v29
	v_mul_f32_e32 v29, v26, v30
	s_waitcnt lgkmcnt(7)
	v_mfma_f32_16x16x32_bf16 v[152:155], v[184:187], v[10:13], v[152:155]
	v_mul_f32_e32 v30, v26, v31
	v_cvt_pk_bf16_f32 v29, v29, v30
	s_waitcnt lgkmcnt(6)
	v_mfma_f32_16x16x32_bf16 v[152:155], v[188:191], v[6:9], v[152:155]
	v_mov_b32_e32 v248, v28
	v_mov_b32_e32 v249, v29
	s_waitcnt lgkmcnt(5)
	v_mfma_f32_16x16x32_bf16 v[152:155], v[172:175], v[2:5], v[152:155]
	v_add_u32_e32 v156, 0xa500, v27
	ds_read2_b64 v[176:179], v156 offset1:4
	ds_read2_b64 v[180:183], v156 offset0:8 offset1:12
	ds_read2_b64 v[184:187], v156 offset0:16 offset1:20
	ds_read2_b64 v[188:191], v156 offset0:24 offset1:28
	ds_read2_b64 v[172:175], v156 offset0:32 offset1:36
	s_waitcnt lgkmcnt(9)
	v_mfma_f32_16x16x32_bf16 v[28:31], v[204:207], v[18:21], 0
	s_nop 3
	v_mul_f32_e32 v152, v26, v152
	v_mul_f32_e32 v153, v26, v153
	s_waitcnt lgkmcnt(8)
	v_mfma_f32_16x16x32_bf16 v[28:31], v[208:211], v[14:17], v[28:31]
	v_cvt_pk_bf16_f32 v152, v152, v153
	v_mul_f32_e32 v153, v26, v154
	s_waitcnt lgkmcnt(7)
	v_mfma_f32_16x16x32_bf16 v[28:31], v[212:215], v[10:13], v[28:31]
	v_mul_f32_e32 v154, v26, v155
	v_cvt_pk_bf16_f32 v153, v153, v154
	s_waitcnt lgkmcnt(6)
; #define LAS __attribute__((address_space(3)))
; __device__ __forceinline__ unsigned cvt_pk_bf16(float lo, float hi) { unsigned r; asm volatile("v_cvt_pk_bf16_f32 %0, %1, %2" : "=v"(r) : "v"(lo), "v"(hi)); return r; }
; __device__ __forceinline__ void attn_item(const Params& P, int half, int item, LAS unsigned char* lds, unsigned* ctr) {
;     ...
;     const float inv = 1.0f / den;
;     bf16_t* op = Z + (size_t)qrow * ZC + colq + 4 * g;
; #pragma unroll
;     for (int dt = 0; dt < 8; ++dt) {
;         f32x4 O = (f32x4){0.f, 0.f, 0.f, 0.f};
;         const LAS unsigned char* vr = Vt + (dt * 16 + c) * VSTR + (m0 + 4 * g) * 2;
; #pragma unroll
;         for (int k5 = 0; k5 < 5; ++k5) { const u32x2 lo = *(const LAS u32x2*)(vr + k5 * 64), hi = *(const LAS u32x2*)(vr + k5 * 64 + 32);
;             const bf16x8 a = as_bf16x8((u32x4){lo.x, lo.y, hi.x, hi.y}); O = __builtin_amdgcn_mfma_f32_16x16x32_bf16(a, Pf[k5], O, 0, 0, 0); }
;         u32x2 ow; ow.x = cvt_pk_bf16(O[0] * inv, O[1] * inv); ow.y = cvt_pk_bf16(O[2] * inv, O[3] * inv);
;         *(u32x2*)(op + dt * 16) = ow;
;     }
;     if (g == 0) LSE[(size_t)qrow * 12 + gi * 4 + hh] = (mx + __builtin_amdgcn_logf(den)) * 0.6931471805599453f;
	v_mfma_f32_16x16x32_bf16 v[28:31], v[216:219], v[6:9], v[28:31]
	v_mov_b32_e32 v154, v152
	v_mov_b32_e32 v155, v153
	v_mov_b32_e32 v152, v248
	v_mov_b32_e32 v153, v249
	s_waitcnt lgkmcnt(5)
	v_mfma_f32_16x16x32_bf16 v[28:31], v[220:223], v[2:5], v[28:31]
	s_nop 1
	v_permlane16_swap_b32_e32 v152, v154
	v_permlane16_swap_b32_e32 v153, v155
	global_store_dwordx4 v[192:193], v[152:155], off offset:64
	s_nop 1
	v_add_u32_e32 v157, 0xc600, v27
	ds_read2_b64 v[204:207], v157 offset1:4
	ds_read2_b64 v[208:211], v157 offset0:8 offset1:12
	ds_read2_b64 v[212:215], v157 offset0:16 offset1:20
	ds_read2_b64 v[216:219], v157 offset0:24 offset1:28
	ds_read2_b64 v[220:223], v157 offset0:32 offset1:36
	s_waitcnt lgkmcnt(9)
	v_mfma_f32_16x16x32_bf16 v[152:155], v[176:179], v[18:21], 0
	s_nop 3
	v_mul_f32_e32 v28, v26, v28
	v_mul_f32_e32 v29, v26, v29
	s_waitcnt lgkmcnt(8)
	v_mfma_f32_16x16x32_bf16 v[152:155], v[180:183], v[14:17], v[152:155]
	v_cvt_pk_bf16_f32 v28, v28, v29
	v_mul_f32_e32 v29, v26, v30
	s_waitcnt lgkmcnt(7)
	v_mfma_f32_16x16x32_bf16 v[152:155], v[184:187], v[10:13], v[152:155]
	v_mul_f32_e32 v30, v26, v31
	v_cvt_pk_bf16_f32 v29, v29, v30
	s_waitcnt lgkmcnt(6)
	v_mfma_f32_16x16x32_bf16 v[152:155], v[188:191], v[6:9], v[152:155]
	v_mov_b32_e32 v248, v28
	v_mov_b32_e32 v249, v29
	s_waitcnt lgkmcnt(5)
	v_mfma_f32_16x16x32_bf16 v[152:155], v[172:175], v[2:5], v[152:155]
	v_add_u32_e32 v156, 0xe700, v27
	ds_read2_b64 v[176:179], v156 offset1:4
	ds_read2_b64 v[180:183], v156 offset0:8 offset1:12
	ds_read2_b64 v[184:187], v156 offset0:16 offset1:20
	ds_read2_b64 v[188:191], v156 offset0:24 offset1:28
	ds_read2_b64 v[172:175], v156 offset0:32 offset1:36
	s_waitcnt lgkmcnt(9)
	v_mfma_f32_16x16x32_bf16 v[28:31], v[204:207], v[18:21], 0
	s_nop 3
	v_mul_f32_e32 v152, v26, v152
	v_mul_f32_e32 v153, v26, v153
	s_waitcnt lgkmcnt(8)
	v_mfma_f32_16x16x32_bf16 v[28:31], v[208:211], v[14:17], v[28:31]
	v_cvt_pk_bf16_f32 v152, v152, v153
	v_mul_f32_e32 v153, v26, v154
	s_waitcnt lgkmcnt(7)
	v_mfma_f32_16x16x32_bf16 v[28:31], v[212:215], v[10:13], v[28:31]
	v_mul_f32_e32 v154, v26, v155
	v_cvt_pk_bf16_f32 v153, v153, v154
	s_waitcnt lgkmcnt(6)
	v_mfma_f32_16x16x32_bf16 v[28:31], v[216:219], v[6:9], v[28:31]
	v_mov_b32_e32 v154, v152
	v_mov_b32_e32 v155, v153
	v_mov_b32_e32 v152, v248
	v_mov_b32_e32 v153, v249
	s_waitcnt lgkmcnt(5)
	v_mfma_f32_16x16x32_bf16 v[28:31], v[220:223], v[2:5], v[28:31]
	s_nop 1
	v_permlane16_swap_b32_e32 v152, v154
	v_permlane16_swap_b32_e32 v153, v155
	global_store_dwordx4 v[192:193], v[152:155], off offset:128
	s_nop 1
	s_waitcnt lgkmcnt(4)
	v_mfma_f32_16x16x32_bf16 v[152:155], v[176:179], v[18:21], 0
	s_nop 3
	v_mul_f32_e32 v28, v26, v28
	v_mul_f32_e32 v29, v26, v29
	s_waitcnt lgkmcnt(3)
	v_mfma_f32_16x16x32_bf16 v[152:155], v[180:183], v[14:17], v[152:155]
	v_cvt_pk_bf16_f32 v28, v28, v29
	v_mul_f32_e32 v29, v26, v30
	s_waitcnt lgkmcnt(2)
	v_mfma_f32_16x16x32_bf16 v[152:155], v[184:187], v[10:13], v[152:155]
	v_mul_f32_e32 v30, v26, v31
	v_cvt_pk_bf16_f32 v29, v29, v30
	s_waitcnt lgkmcnt(1)
	v_mfma_f32_16x16x32_bf16 v[152:155], v[188:191], v[6:9], v[152:155]
	v_mov_b32_e32 v248, v28
	v_mov_b32_e32 v249, v29
	s_waitcnt lgkmcnt(0)
	v_mfma_f32_16x16x32_bf16 v[152:155], v[172:175], v[2:5], v[152:155]
	s_nop 7
	s_nop 3
	v_mul_f32_e32 v152, v26, v152
	v_mul_f32_e32 v153, v26, v153
	v_cvt_pk_bf16_f32 v152, v152, v153
	v_mul_f32_e32 v153, v26, v154
	v_mul_f32_e32 v154, v26, v155
	v_cvt_pk_bf16_f32 v153, v153, v154
	v_mov_b32_e32 v154, v152
	v_mov_b32_e32 v155, v153
	v_mov_b32_e32 v152, v248
	v_mov_b32_e32 v153, v249
	s_nop 1
	v_permlane16_swap_b32_e32 v152, v154
	v_permlane16_swap_b32_e32 v153, v155
	global_store_dwordx4 v[192:193], v[152:155], off offset:192
	s_nop 1
	s_and_saveexec_b64 s[30:31], vcc
	s_cbranch_execz .LBB0_541
	v_log_f32_e32 v2, v25
	v_readlane_b32 s8, v251, 33
	s_lshl_b32 s6, s2, 2
	v_readlane_b32 s9, v251, 34
	v_add_f32_e32 v2, v24, v2
	s_ashr_i32 s7, s6, 31
	v_mul_f32_e32 v4, 0x3f317218, v2
	v_mad_i64_i32 v[2:3], s[8:9], v133, 48, s[8:9]
	v_lshl_add_u64 v[2:3], s[6:7], 2, v[2:3]
	s_lshl_b32 s20, s4, 2
	v_lshl_add_u64 v[2:3], v[2:3], 0, s[20:21]
	global_store_dword v[2:3], v4, off
